# L1-P3: the block's conv weight/bias vectors (same 64 channels for all its tiles) are fetched once before the tile loop
# baseline (speedup 1.0000x reference)
.LBB0_1292:
	s_or_b64 exec, exec, s[6:7]
	s_waitcnt lgkmcnt(0)
	v_mov_b32_e32 v0, v254
	v_mov_b64_e32 v[2:3], s[40:41]
	s_barrier
	flat_load_dwordx2 v[4:5], v[2:3] offset:248 sc0 sc1
	flat_load_dwordx2 v[6:7], v[2:3] offset:256 sc0 sc1
	s_waitcnt vmcnt(0)
	s_add_u32 s46, s26, 0xd200000
	s_addc_u32 s47, s27, 0
	s_add_u32 s54, s26, 0x9200000
	s_addc_u32 s55, s27, 0
	s_cmpk_lt_i32 s2, 0x1000
	s_waitcnt lgkmcnt(0)
	v_readfirstlane_b32 s9, v5
	v_readfirstlane_b32 s8, v4
	v_readfirstlane_b32 s11, v7
	v_readfirstlane_b32 s10, v6
	s_cbranch_scc0 .LBB0_1319
	v_ashrrev_i32_e32 v5, 4, v0
	v_lshlrev_b32_e32 v1, 2, v0
	v_ashrrev_i32_e32 v55, 3, v0
	v_lshlrev_b32_e32 v0, 3, v0
	s_add_u32 s12, s8, 0x6000
	v_and_b32_e32 v4, 56, v0
	s_movk_i32 s4, 0x41
	v_and_b32_e32 v54, 60, v1
	s_addc_u32 s13, s9, 0
	v_mad_u64_u32 v[0:1], s[0:1], v55, s4, v[4:5]
	s_add_u32 s14, s8, 0xc000
	v_lshl_add_u32 v56, v0, 2, 0
	v_mad_u32_u24 v0, v54, s4, v5
	s_addc_u32 s15, s9, 0
	v_mov_b32_e32 v7, 0
	v_or_b32_e32 v57, 0x800, v54
	v_or_b32_e32 v58, 0x1000, v54
	v_lshl_add_u32 v59, v0, 2, 0
	s_lshl_b32 s4, s2, 1
	s_lshl_b32 s5, s30, 1
	s_lshl_b32 s18, s2, 6
	s_lshl_b32 s19, s30, 6
	s_movk_i32 s20, 0x3000
	v_mov_b64_e32 v[8:9], s[48:49]
	s_movk_i32 s21, 0x1fff
	s_mov_b32 s23, 0xd200000
	s_mov_b32 s24, s2
	s_and_b32 s17, s18, 0x7c0
	v_or_b32_e32 v0, s17, v54
	v_lshlrev_b32_e32 v6, 2, v0
	v_add_u32_e32 v172, 0x2000, v6
	v_add_u32_e32 v173, 0x4000, v6
	global_load_dwordx4 v[118:121], v6, s[12:13]
	global_load_dwordx4 v[122:125], v172, s[12:13]
	global_load_dwordx4 v[126:129], v173, s[12:13]
	global_load_dwordx4 v[142:145], v6, s[10:11]
	global_load_dwordx4 v[146:149], v172, s[10:11]
	global_load_dwordx4 v[150:153], v173, s[10:11]
	global_load_dwordx4 v[130:133], v6, s[14:15]
	global_load_dwordx4 v[134:137], v172, s[14:15]
	global_load_dwordx4 v[138:141], v173, s[14:15]
	global_load_dwordx4 v[106:109], v6, s[8:9]
	global_load_dwordx4 v[110:113], v172, s[8:9]
	global_load_dwordx4 v[114:117], v173, s[8:9]
	s_branch .LBB0_1295

.LBB0_1295:
	s_and_b32 s16, s4, 0xffffffc0
	s_and_b32 s17, s18, 0x7c0
	v_add_u32_e32 v60, s16, v5
	v_or_b32_e32 v0, s17, v54
	v_mad_i64_i32 v[32:33], s[0:1], v60, s20, v[8:9]
	v_lshlrev_b32_e32 v10, 1, v0
	v_mov_b32_e32 v11, v7
	v_lshlrev_b32_e32 v6, 2, v0
	v_mul_u32_u24_e32 v154, 0x3000, v60
	v_max_i32_e32 v155, 1, v60
	v_add_u32_e32 v154, v154, v10
	v_add_u32_e32 v155, -1, v155
	v_mul_u32_u24_e32 v155, 0x3000, v155
	v_add_u32_e32 v155, v155, v10
	global_load_dwordx2 v[70:71], v155, s[48:49]
	v_add_u32_e32 v156, 0x1000, v155
	global_load_dwordx2 v[72:73], v156, s[48:49]
	v_add_u32_e32 v157, 0x2000, v155
	global_load_dwordx2 v[74:75], v157, s[48:49]
	global_load_dwordx2 v[76:77], v154, s[48:49]
	v_add_u32_e32 v158, 0x1000, v154
	global_load_dwordx2 v[78:79], v158, s[48:49]
	v_add_u32_e32 v159, 0x2000, v154
	global_load_dwordx2 v[80:81], v159, s[48:49]
	v_add_u32_e32 v160, 0x3000, v154
	global_load_dwordx2 v[82:83], v160, s[48:49]
	v_add_u32_e32 v161, 0x4000, v154
	global_load_dwordx2 v[84:85], v161, s[48:49]
	v_add_u32_e32 v162, 0x5000, v154
	global_load_dwordx2 v[86:87], v162, s[48:49]
	v_add_u32_e32 v163, 0x5d000, v154
	global_load_dwordx2 v[88:89], v163, s[48:49]
	v_add_u32_e32 v164, 0x5e000, v154
	global_load_dwordx2 v[90:91], v164, s[48:49]
	v_add_u32_e32 v165, 0x5f000, v154
	global_load_dwordx2 v[92:93], v165, s[48:49]
	v_add_u32_e32 v166, 0x60000, v154
	global_load_dwordx2 v[94:95], v166, s[48:49]
	v_add_u32_e32 v167, 0x61000, v154
	global_load_dwordx2 v[96:97], v167, s[48:49]
	v_add_u32_e32 v168, 0x62000, v154
	global_load_dwordx2 v[98:99], v168, s[48:49]
	v_add_u32_e32 v169, 0x63000, v154
	global_load_dwordx2 v[100:101], v169, s[48:49]
	v_add_u32_e32 v170, 0x64000, v154
	global_load_dwordx2 v[102:103], v170, s[48:49]
	v_add_u32_e32 v171, 0x65000, v154
	global_load_dwordx2 v[104:105], v171, s[48:49]
	s_waitcnt vmcnt(0)
	v_lshl_add_u64 v[0:1], v[32:33], 0, v[10:11]
	v_mov_b64_e32 v[26:27], v[76:77]
	v_lshl_add_u64 v[20:21], s[12:13], 0, v[6:7]
	v_lshl_add_u64 v[24:25], s[10:11], 0, v[6:7]
	v_mov_b64_e32 v[12:13], v[118:119]
	v_mov_b64_e32 v[14:15], v[120:121]
	v_mov_b64_e32 v[16:17], v[142:143]
	v_mov_b64_e32 v[18:19], v[144:145]
	v_lshl_add_u64 v[22:23], s[14:15], 0, v[6:7]
	v_mov_b64_e32 v[0:1], v[130:131]
	v_mov_b64_e32 v[2:3], v[132:133]
	v_add_u32_e32 v28, -1, v60
	v_mad_u64_u32 v[42:43], s[0:1], v28, s20, v[8:9]
	v_cmp_lt_i32_e32 vcc, 0, v60
	s_waitcnt vmcnt(0)
	v_lshlrev_b32_e32 v28, 16, v26
	v_and_b32_e32 v29, 0xffff0000, v26
	v_lshlrev_b32_e32 v26, 16, v27
	v_and_b32_e32 v27, 0xffff0000, v27
	s_waitcnt lgkmcnt(0)
	v_pk_fma_f32 v[38:39], v[14:15], v[26:27], v[18:19]
	v_pk_fma_f32 v[40:41], v[12:13], v[28:29], v[16:17]
	s_and_saveexec_b64 s[0:1], vcc
	s_cbranch_execz .LBB0_1297
	v_lshl_add_u64 v[12:13], v[42:43], 0, v[10:11]
	v_mov_b64_e32 v[16:17], v[70:71]
	v_lshl_add_u64 v[12:13], s[8:9], 0, v[6:7]
	v_mov_b64_e32 v[12:13], v[106:107]
	v_mov_b64_e32 v[14:15], v[108:109]
	s_waitcnt vmcnt(0)
	v_lshlrev_b32_e32 v18, 16, v16
	v_and_b32_e32 v19, 0xffff0000, v16
	v_lshlrev_b32_e32 v16, 16, v17
	v_and_b32_e32 v17, 0xffff0000, v17
	s_waitcnt lgkmcnt(0)
	v_pk_fma_f32 v[38:39], v[14:15], v[16:17], v[38:39]
	v_pk_fma_f32 v[40:41], v[12:13], v[18:19], v[40:41]
